# v40 stack + one mid-burst priority flip (after 8 of 16 MFMAs) in the fp8 K-loops
# speedup vs baseline: 1.0034x; 1.0034x over previous
; #define PG8_LDA(dst, b, h) do { if constexpr (FP8) { _Pragma("unroll") for (int m = 0; m < 4; ++m) dst##8[m] = PG8_LD8(PG8_SA(b, h), aoff, aoff1, m); } \
;         else { _Pragma("unroll") for (int m = 0; m < 4; ++m) _Pragma("unroll") for (int k = 0; k < 2; ++k) dst[m][k] = *(const LAS bf16x8*)(lds + PG8_SA(b, h) + (k ? aoff1 : aoff) + m * 2048); } } while (0)
; #define PG8_LDB(dst, b, h) do { if constexpr (FP8) { dst##8[0] = PG8_LD8(PG8_SB(b, h), boff, boff1, 0); dst##8[1] = PG8_LD8(PG8_SB(b, h), boff, boff1, 1); } \
;         else { _Pragma("unroll") for (int n = 0; n < 2; ++n) _Pragma("unroll") for (int k = 0; k < 2; ++k) dst[n][k] = *(const LAS bf16x8*)(lds + PG8_SB(b, h) + (k ? boff1 : boff) + n * 2048); } } while (0)
; #define PG8_WAIT_V(n) asm volatile("s_waitcnt vmcnt(" #n ")" ::: "memory")
; #define PG8_WAIT_L(n) asm volatile("s_waitcnt lgkmcnt(" #n ")" ::: "memory")
; #define PG8_BAR __builtin_amdgcn_s_barrier()
; #define PG8_SCHED __builtin_amdgcn_sched_barrier(0)
; #define PG8_S1 PG8_STAGE(PG8_SA(1, 1), a1 + hstepA, voffA)
; #define PG8_S2 do { PG8_STAGE(PG8_SB(0, 0), b2, voffB); PG8_STAGE(PG8_SB(0, 1), b2 + hstepB, voffB); PG8_STAGE(PG8_SA(0, 0), a2, voffA); } while (0)
; template <class Epi, class SchedT, bool ALIGN_EPI, bool SP2, bool FP8 = false>
; __device__ __forceinline__ void gemm_phase(LAS unsigned char* lds, const Gemm g, const SchedT& S, const Epi& E, const int wid) {
;     ...
;         for (int t = 0; t < nt; t += 2) {
;             const bool last = (t == nt - 2);
;             const char* a1 = cA + (size_t)(t + 1) * kstep;
;             const char* a2 = last ? nA : cA + (size_t)(t + 2) * kstep; const char* b2 = last ? nB : cB + (size_t)(t + 2) * kstep;
;             const char* a3 = a2 + kstep; const char* b3 = b2 + kstep;
;             if constexpr (SP2) {
;     ...
;             PG8_LDB(B0, 0, 0); PG8_LDB(B1, 0, 1); PG8_SCHED; PG8_LDA(At, 0, 0); PG8_S1;
;             PG8_WAIT_V(8); PG8_WAIT_L(0); PG8_BAR; PG8_MMAP(0, 0, 0); PG8_BAR; PG8_SCHED;
;             PG8_LDA(At, 0, 1); PG8_S2;
;             PG8_WAIT_V(8); PG8_WAIT_L(0); PG8_BAR; PG8_MMAP(1, 0, 1); PG8_BAR; PG8_SCHED;
.LBB0_239:
	ds_read_b128 v[130:133], v143
	ds_read_b128 v[134:137], v143 offset:16
	ds_read_b128 v[148:151], v143 offset:2048
	ds_read_b128 v[152:155], v143 offset:2064
	ds_read_b128 v[156:159], v144
	ds_read_b128 v[160:163], v144 offset:16
	ds_read_b128 v[164:167], v144 offset:2048
	ds_read_b128 v[168:171], v144 offset:2064
	s_add_i32 s30, s31, 2
	s_add_u32 s6, s52, 0xfff70080
	s_addc_u32 s7, s53, -1
	s_cmp_eq_u32 s20, s31
	s_cselect_b32 s67, s49, s7
	s_cselect_b32 s66, s48, s6
	v_mov_b32_e32 v128, v138
	ds_read_b128 v[172:175], v145
	ds_read_b128 v[176:179], v145 offset:16
	ds_read_b128 v[180:183], v145 offset:2048
	ds_read_b128 v[184:187], v145 offset:2064
	ds_read_b128 v[188:191], v145 offset:4096
	ds_read_b128 v[192:195], v145 offset:4112
	ds_read_b128 v[196:199], v145 offset:6144
	ds_read_b128 v[200:203], v145 offset:6160
	s_cselect_b32 s69, s8, s24
	s_cselect_b32 s68, s9, s21
	s_add_i32 m0, s87, 0xc000
	s_nop 0
	global_load_lds_dwordx4 v128, s[52:53]
	v_mov_b32_e32 v128, v140
	s_add_i32 m0, s87, 0xe000
	s_nop 0
	global_load_lds_dwordx4 v128, s[52:53]
	s_waitcnt vmcnt(8)
	s_waitcnt lgkmcnt(0)
	s_barrier
	s_setprio 1
	s_waitcnt lgkmcnt(0)
	v_mfma_scale_f32_16x16x128_f8f6f4 v[124:127], v[130:137], v[172:179], v[124:127], v146, v146 op_sel_hi:[0,0,0]
	v_mfma_scale_f32_16x16x128_f8f6f4 v[108:111], v[156:163], v[172:179], v[108:111], v146, v146 op_sel_hi:[0,0,0]
	v_mfma_scale_f32_16x16x128_f8f6f4 v[120:123], v[148:155], v[172:179], v[120:123], v146, v146 op_sel_hi:[0,0,0]
	v_mfma_scale_f32_16x16x128_f8f6f4 v[100:103], v[164:171], v[172:179], v[100:103], v146, v146 op_sel_hi:[0,0,0]
	v_mfma_scale_f32_16x16x128_f8f6f4 v[116:119], v[130:137], v[180:187], v[116:119], v146, v146 op_sel_hi:[0,0,0]
	v_mfma_scale_f32_16x16x128_f8f6f4 v[112:115], v[148:155], v[180:187], v[112:115], v146, v146 op_sel_hi:[0,0,0]
	v_mfma_scale_f32_16x16x128_f8f6f4 v[104:107], v[130:137], v[188:195], v[104:107], v146, v146 op_sel_hi:[0,0,0]
	v_mfma_scale_f32_16x16x128_f8f6f4 v[60:63], v[164:171], v[196:203], v[60:63], v146, v146 op_sel_hi:[0,0,0]
	s_setprio 0
	s_setprio 1
	v_mfma_scale_f32_16x16x128_f8f6f4 v[172:175], v[156:163], v[180:187], v[92:95], v146, v146 op_sel_hi:[0,0,0]
	v_mfma_scale_f32_16x16x128_f8f6f4 v[176:179], v[164:171], v[180:187], v[84:87], v146, v146 op_sel_hi:[0,0,0]
	v_mfma_scale_f32_16x16x128_f8f6f4 v[180:183], v[156:163], v[188:195], v[76:79], v146, v146 op_sel_hi:[0,0,0]
	v_mfma_scale_f32_16x16x128_f8f6f4 v[184:187], v[148:155], v[188:195], v[96:99], v146, v146 op_sel_hi:[0,0,0]
	v_mfma_scale_f32_16x16x128_f8f6f4 v[188:191], v[164:171], v[188:195], v[72:75], v146, v146 op_sel_hi:[0,0,0]
	v_mfma_scale_f32_16x16x128_f8f6f4 v[192:195], v[130:137], v[196:203], v[88:91], v146, v146 op_sel_hi:[0,0,0]
	v_mfma_scale_f32_16x16x128_f8f6f4 v[204:207], v[156:163], v[196:203], v[68:71], v146, v146 op_sel_hi:[0,0,0]
	v_mfma_scale_f32_16x16x128_f8f6f4 v[208:211], v[148:155], v[196:203], v[80:83], v146, v146 op_sel_hi:[0,0,0]
	s_setprio 0
	s_barrier
	v_mov_b32_e32 v128, v139
	s_add_i32 s6, s94, s86
	s_nop 1
	ds_read_b128 v[68:71], v145 offset:16384
	ds_read_b128 v[72:75], v145 offset:16400
	ds_read_b128 v[76:79], v145 offset:18432
	ds_read_b128 v[80:83], v145 offset:18448
	ds_read_b128 v[84:87], v145 offset:20480
	ds_read_b128 v[88:91], v145 offset:20496
	ds_read_b128 v[92:95], v145 offset:22528
	ds_read_b128 v[96:99], v145 offset:22544
	s_mov_b32 m0, s6
	s_nop 0
	global_load_lds_dwordx4 v128, s[68:69]
	v_mov_b32_e32 v128, v141
	s_add_i32 m0, s6, 0x2000
	s_add_u32 s38, s68, 0x20000
	global_load_lds_dwordx4 v128, s[68:69]
	s_addc_u32 s39, s69, 0
	v_mov_b32_e32 v128, v139
	s_add_i32 s6, s95, s86
	s_mov_b32 m0, s6
	s_nop 0
	global_load_lds_dwordx4 v128, s[38:39]
	v_mov_b32_e32 v128, v141
	s_add_i32 m0, s6, 0x2000
	s_nop 0
	global_load_lds_dwordx4 v128, s[38:39]
	v_mov_b32_e32 v128, v138
	s_mov_b32 m0, s87
	s_nop 0
	global_load_lds_dwordx4 v128, s[66:67]
	v_mov_b32_e32 v128, v140
	s_mov_b32 m0, s88
	s_nop 0
	global_load_lds_dwordx4 v128, s[66:67]
	s_waitcnt vmcnt(8)
	s_waitcnt lgkmcnt(0)
	s_barrier
	s_setprio 1
	s_waitcnt lgkmcnt(0)
	v_mfma_scale_f32_16x16x128_f8f6f4 v[64:67], v[130:137], v[68:75], v[64:67], v146, v146 op_sel_hi:[0,0,0]
	v_mfma_scale_f32_16x16x128_f8f6f4 v[44:47], v[156:163], v[68:75], v[44:47], v146, v146 op_sel_hi:[0,0,0]
	v_mfma_scale_f32_16x16x128_f8f6f4 v[56:59], v[148:155], v[68:75], v[56:59], v146, v146 op_sel_hi:[0,0,0]
	v_mfma_scale_f32_16x16x128_f8f6f4 v[52:55], v[130:137], v[76:83], v[52:55], v146, v146 op_sel_hi:[0,0,0]
	v_mfma_scale_f32_16x16x128_f8f6f4 v[48:51], v[148:155], v[76:83], v[48:51], v146, v146 op_sel_hi:[0,0,0]
	v_mfma_scale_f32_16x16x128_f8f6f4 v[40:43], v[130:137], v[84:91], v[40:43], v146, v146 op_sel_hi:[0,0,0]
	v_mfma_scale_f32_16x16x128_f8f6f4 v[196:199], v[164:171], v[68:75], v[36:39], v146, v146 op_sel_hi:[0,0,0]
	v_mfma_scale_f32_16x16x128_f8f6f4 v[200:203], v[156:163], v[76:83], v[28:31], v146, v146 op_sel_hi:[0,0,0]
	s_setprio 0
	s_setprio 1
	v_mfma_scale_f32_16x16x128_f8f6f4 v[212:215], v[164:171], v[76:83], v[20:23], v146, v146 op_sel_hi:[0,0,0]
	v_mfma_scale_f32_16x16x128_f8f6f4 v[216:219], v[156:163], v[84:91], v[12:15], v146, v146 op_sel_hi:[0,0,0]
	v_mfma_scale_f32_16x16x128_f8f6f4 v[220:223], v[148:155], v[84:91], v[32:35], v146, v146 op_sel_hi:[0,0,0]
	v_mfma_scale_f32_16x16x128_f8f6f4 v[224:227], v[164:171], v[84:91], v[8:11], v146, v146 op_sel_hi:[0,0,0]
	v_mfma_scale_f32_16x16x128_f8f6f4 v[228:231], v[130:137], v[92:99], v[24:27], v146, v146 op_sel_hi:[0,0,0]
	v_mfma_scale_f32_16x16x128_f8f6f4 v[232:235], v[156:163], v[92:99], v[4:7], v146, v146 op_sel_hi:[0,0,0]
	v_mfma_scale_f32_16x16x128_f8f6f4 v[236:239], v[148:155], v[92:99], v[16:19], v146, v146 op_sel_hi:[0,0,0]
	v_mfma_scale_f32_16x16x128_f8f6f4 v[240:243], v[164:171], v[92:99], v[0:3], v146, v146 op_sel_hi:[0,0,0]
	s_setprio 0
	s_barrier
; #define PG8_LDA(dst, b, h) do { if constexpr (FP8) { _Pragma("unroll") for (int m = 0; m < 4; ++m) dst##8[m] = PG8_LD8(PG8_SA(b, h), aoff, aoff1, m); } \
;         else { _Pragma("unroll") for (int m = 0; m < 4; ++m) _Pragma("unroll") for (int k = 0; k < 2; ++k) dst[m][k] = *(const LAS bf16x8*)(lds + PG8_SA(b, h) + (k ? aoff1 : aoff) + m * 2048); } } while (0)
; #define PG8_LDB(dst, b, h) do { if constexpr (FP8) { dst##8[0] = PG8_LD8(PG8_SB(b, h), boff, boff1, 0); dst##8[1] = PG8_LD8(PG8_SB(b, h), boff, boff1, 1); } \
;         else { _Pragma("unroll") for (int n = 0; n < 2; ++n) _Pragma("unroll") for (int k = 0; k < 2; ++k) dst[n][k] = *(const LAS bf16x8*)(lds + PG8_SB(b, h) + (k ? boff1 : boff) + n * 2048); } } while (0)
; #define PG8_WAIT_V(n) asm volatile("s_waitcnt vmcnt(" #n ")" ::: "memory")
; #define PG8_WAIT_L(n) asm volatile("s_waitcnt lgkmcnt(" #n ")" ::: "memory")
; #define PG8_BAR __builtin_amdgcn_s_barrier()
; #define PG8_SCHED __builtin_amdgcn_sched_barrier(0)
; #define PG8_S3 PG8_STAGE(PG8_SA(0, 1), a2 + hstepA, voffA)
; #define PG8_S4 do { PG8_STAGE(PG8_SB(1, 0), b3, voffB); PG8_STAGE(PG8_SB(1, 1), b3 + hstepB, voffB); PG8_STAGE(PG8_SA(1, 0), a3, voffA); } while (0)
; template <class Epi, class SchedT, bool ALIGN_EPI, bool SP2, bool FP8 = false>
; __device__ __forceinline__ void gemm_phase(LAS unsigned char* lds, const Gemm g, const SchedT& S, const Epi& E, const int wid) {
;     ...
;             PG8_LDB(B0, 1, 0); PG8_LDB(B1, 1, 1); PG8_SCHED; PG8_LDA(At, 1, 0); PG8_S3;
;             PG8_WAIT_V(8); PG8_WAIT_L(0); PG8_BAR; PG8_MMAP(0, 1, 0); PG8_BAR; PG8_SCHED;
;             PG8_LDA(At, 1, 1); PG8_S4;
	s_add_i32 s6, 0, 0x18000
	v_add_u32_e32 v8, s6, v142
	s_add_i32 s7, 0, 0x1c000
	s_nop 1
	ds_read_b128 v[0:3], v8
	ds_read_b128 v[4:7], v8 offset:16
	ds_read_b128 v[130:133], v8 offset:2048
	ds_read_b128 v[134:137], v8 offset:2064
	v_add_u32_e32 v8, s7, v142
	ds_read_b128 v[148:151], v8
	ds_read_b128 v[152:155], v8 offset:16
	ds_read_b128 v[156:159], v8 offset:2048
	ds_read_b128 v[160:163], v8 offset:2064
	s_add_u32 s38, s66, 0x90000
	v_mov_b32_e32 v68, v138
	s_mov_b32 m0, s89
	ds_read_b128 v[8:11], v145 offset:32768
	ds_read_b128 v[12:15], v145 offset:32784
	ds_read_b128 v[16:19], v145 offset:34816
	ds_read_b128 v[20:23], v145 offset:34832
	ds_read_b128 v[24:27], v145 offset:36864
	ds_read_b128 v[28:31], v145 offset:36880
	ds_read_b128 v[32:35], v145 offset:38912
	ds_read_b128 v[36:39], v145 offset:38928
	s_addc_u32 s39, s67, 0
	s_nop 0
	global_load_lds_dwordx4 v68, s[38:39]
	v_mov_b32_e32 v68, v140
	s_mov_b32 m0, s90
	s_nop 0
	global_load_lds_dwordx4 v68, s[38:39]
	s_waitcnt vmcnt(8)
	s_waitcnt lgkmcnt(0)
	s_barrier
	s_setprio 1
	s_waitcnt lgkmcnt(0)
	v_mfma_scale_f32_16x16x128_f8f6f4 v[124:127], v[0:7], v[8:15], v[124:127], v146, v146 op_sel_hi:[0,0,0]
	v_mfma_scale_f32_16x16x128_f8f6f4 v[108:111], v[148:155], v[8:15], v[108:111], v146, v146 op_sel_hi:[0,0,0]
	v_mfma_scale_f32_16x16x128_f8f6f4 v[120:123], v[130:137], v[8:15], v[120:123], v146, v146 op_sel_hi:[0,0,0]
	v_mfma_scale_f32_16x16x128_f8f6f4 v[100:103], v[156:163], v[8:15], v[100:103], v146, v146 op_sel_hi:[0,0,0]
	v_mfma_scale_f32_16x16x128_f8f6f4 v[116:119], v[0:7], v[16:23], v[116:119], v146, v146 op_sel_hi:[0,0,0]
	v_mfma_scale_f32_16x16x128_f8f6f4 v[92:95], v[148:155], v[16:23], v[172:175], v146, v146 op_sel_hi:[0,0,0]
	v_mfma_scale_f32_16x16x128_f8f6f4 v[112:115], v[130:137], v[16:23], v[112:115], v146, v146 op_sel_hi:[0,0,0]
	v_mfma_scale_f32_16x16x128_f8f6f4 v[84:87], v[156:163], v[16:23], v[176:179], v146, v146 op_sel_hi:[0,0,0]
	s_setprio 0
	s_setprio 1
	v_mfma_scale_f32_16x16x128_f8f6f4 v[104:107], v[0:7], v[24:31], v[104:107], v146, v146 op_sel_hi:[0,0,0]
	v_mfma_scale_f32_16x16x128_f8f6f4 v[76:79], v[148:155], v[24:31], v[180:183], v146, v146 op_sel_hi:[0,0,0]
	v_mfma_scale_f32_16x16x128_f8f6f4 v[96:99], v[130:137], v[24:31], v[184:187], v146, v146 op_sel_hi:[0,0,0]
	v_mfma_scale_f32_16x16x128_f8f6f4 v[72:75], v[156:163], v[24:31], v[188:191], v146, v146 op_sel_hi:[0,0,0]
	v_mfma_scale_f32_16x16x128_f8f6f4 v[88:91], v[0:7], v[32:39], v[192:195], v146, v146 op_sel_hi:[0,0,0]
	v_mfma_scale_f32_16x16x128_f8f6f4 v[68:71], v[148:155], v[32:39], v[204:207], v146, v146 op_sel_hi:[0,0,0]
	v_mfma_scale_f32_16x16x128_f8f6f4 v[80:83], v[130:137], v[32:39], v[208:211], v146, v146 op_sel_hi:[0,0,0]
	v_mfma_scale_f32_16x16x128_f8f6f4 v[60:63], v[156:163], v[32:39], v[60:63], v146, v146 op_sel_hi:[0,0,0]
	s_setprio 0
	s_barrier
	v_mov_b32_e32 v128, v139
	ds_read_b128 v[8:11], v145 offset:49152
	ds_read_b128 v[12:15], v145 offset:49168
	ds_read_b128 v[16:19], v145 offset:51200
	ds_read_b128 v[20:23], v145 offset:51216
	ds_read_b128 v[164:167], v145 offset:53248
	ds_read_b128 v[168:171], v145 offset:53264
	ds_read_b128 v[172:175], v145 offset:55296
	ds_read_b128 v[176:179], v145 offset:55312
	s_add_i32 s6, s6, s86
	v_lshl_add_u64 v[24:25], s[68:69], 0, v[128:129]
	v_lshl_add_u64 v[24:25], v[24:25], 0, s[40:41]
	s_mov_b32 m0, s6
	v_mov_b32_e32 v128, v141
	global_load_lds_dwordx4 v[24:25], off
	s_add_i32 m0, s6, 0x2000
	v_lshl_add_u64 v[24:25], s[68:69], 0, v[128:129]
	v_lshl_add_u64 v[24:25], v[24:25], 0, s[40:41]
	s_add_u32 s38, s68, 0x20080
	global_load_lds_dwordx4 v[24:25], off
	s_addc_u32 s39, s69, 0
	v_mov_b32_e32 v24, v139
	s_add_i32 s6, s7, s86
	s_mov_b32 m0, s6
	v_mov_b32_e32 v128, v138
	global_load_lds_dwordx4 v24, s[38:39]
	v_mov_b32_e32 v24, v141
	s_add_i32 m0, s6, 0x2000
	s_nop 0
	global_load_lds_dwordx4 v24, s[38:39]
	s_mov_b32 m0, s92
	v_lshl_add_u64 v[24:25], s[66:67], 0, v[128:129]
	v_lshl_add_u64 v[24:25], v[24:25], 0, s[40:41]
	v_mov_b32_e32 v128, v140
	global_load_lds_dwordx4 v[24:25], off
	s_mov_b32 m0, s93
	v_lshl_add_u64 v[24:25], s[66:67], 0, v[128:129]
	v_lshl_add_u64 v[24:25], v[24:25], 0, s[40:41]
	global_load_lds_dwordx4 v[24:25], off
	s_waitcnt vmcnt(8)
	s_waitcnt lgkmcnt(0)
	s_barrier
; #define PG8_WAIT_V(n) asm volatile("s_waitcnt vmcnt(" #n ")" ::: "memory")
; #define PG8_WAIT_L(n) asm volatile("s_waitcnt lgkmcnt(" #n ")" ::: "memory")
;     __device__ __forceinline__ void operator()(const f32x4 (&acc)[2][2][4][2], const Unit& u, int wr, int wc, int fr, int fq) const {
;     ...
;             for (int m = 0; m < 4; ++m) { bf16_t* rowp = O + (size_t)(row0 + ai * HALF + m * 16) * ldc + col0;
; #pragma unroll
;                 for (int bj = 0; bj < 2; ++bj) { const f32x4 v0 = acc[ai][bj][m][0] * sc, v1 = acc[ai][bj][m][1] * sc;
;                     u32x4 w; w.x = pk2(v0[0], v0[1]); w.y = pk2(v0[2], v0[3]); w.z = pk2(v1[0], v1[1]); w.w = pk2(v1[2], v1[3]);
;                     *(u32x4*)(rowp + bj * HALF) = w; } }
; template <class Epi, class SchedT, bool ALIGN_EPI, bool SP2, bool FP8 = false>
; __device__ __forceinline__ void gemm_phase(LAS unsigned char* lds, const Gemm g, const SchedT& S, const Epi& E, const int wid) {
;     ...
;             PG8_WAIT_V(8); PG8_WAIT_L(0); PG8_BAR; PG8_MMAP(1, 1, 1); PG8_BAR; PG8_SCHED;
;             } else {
;             PG8_LDB(B0, 0, 0); PG8_SCHED; PG8_LDA(At, 0, 0); PG8_STAGE(PG8_SA(1, 1), a1 + hstepA, voffA);
;             PG8_WAIT_L(8); PG8_BAR; PG8_WAIT_L(0); PG8_MMA(0, 0, At, B0); PG8_BAR; PG8_SCHED;
;             PG8_LDB(B1, 0, 1); PG8_STAGE(PG8_SB(0, 0), b2, voffB);
;             PG8_BAR; PG8_WAIT_L(0); PG8_MMA(0, 1, At, B1); PG8_BAR;
;             PG8_LDA(At, 0, 1); PG8_STAGE(PG8_SA(0, 0), a2, voffA);
;             PG8_BAR; PG8_WAIT_L(0); PG8_MMA(1, 0, At, B0); PG8_BAR; PG8_SCHED;
;             PG8_STAGE(PG8_SB(0, 1), b2 + hstepB, voffB);
;             PG8_WAIT_V(6); PG8_BAR; PG8_MMA(1, 1, At, B1); PG8_BAR;
;             PG8_LDB(B0, 1, 0); PG8_SCHED; PG8_LDA(At, 1, 0); PG8_STAGE(PG8_SA(0, 1), a2 + hstepA, voffA);
;             PG8_WAIT_L(8); PG8_BAR; PG8_WAIT_L(0); PG8_MMA(0, 0, At, B0); PG8_BAR; PG8_SCHED;
;             PG8_LDB(B1, 1, 1); PG8_STAGE(PG8_SB(1, 0), b3, voffB);
;             PG8_BAR; PG8_WAIT_L(0); PG8_MMA(0, 1, At, B1); PG8_BAR;
;             PG8_LDA(At, 1, 1); PG8_STAGE(PG8_SA(1, 0), a3, voffA);
;             PG8_BAR; PG8_WAIT_L(0); PG8_MMA(1, 0, At, B0); PG8_BAR; PG8_SCHED;
;             PG8_STAGE(PG8_SB(1, 1), b3 + hstepB, voffB);
;             PG8_WAIT_V(6); PG8_BAR; PG8_MMA(1, 1, At, B1); PG8_BAR;
;             }
;         }
;         if constexpr (ALIGN_EPI) { if (wr == 0) PG8_BAR; }
	s_setprio 1
	s_waitcnt lgkmcnt(0)
	v_mfma_scale_f32_16x16x128_f8f6f4 v[64:67], v[0:7], v[8:15], v[64:67], v146, v146 op_sel_hi:[0,0,0]
	v_mfma_scale_f32_16x16x128_f8f6f4 v[44:47], v[148:155], v[8:15], v[44:47], v146, v146 op_sel_hi:[0,0,0]
	v_mfma_scale_f32_16x16x128_f8f6f4 v[56:59], v[130:137], v[8:15], v[56:59], v146, v146 op_sel_hi:[0,0,0]
	v_mfma_scale_f32_16x16x128_f8f6f4 v[36:39], v[156:163], v[8:15], v[196:199], v146, v146 op_sel_hi:[0,0,0]
	v_mfma_scale_f32_16x16x128_f8f6f4 v[52:55], v[0:7], v[16:23], v[52:55], v146, v146 op_sel_hi:[0,0,0]
	v_mfma_scale_f32_16x16x128_f8f6f4 v[28:31], v[148:155], v[16:23], v[200:203], v146, v146 op_sel_hi:[0,0,0]
	v_mfma_scale_f32_16x16x128_f8f6f4 v[48:51], v[130:137], v[16:23], v[48:51], v146, v146 op_sel_hi:[0,0,0]
	v_mfma_scale_f32_16x16x128_f8f6f4 v[20:23], v[156:163], v[16:23], v[212:215], v146, v146 op_sel_hi:[0,0,0]
	s_setprio 0
	s_setprio 1
	v_mfma_scale_f32_16x16x128_f8f6f4 v[40:43], v[0:7], v[164:171], v[40:43], v146, v146 op_sel_hi:[0,0,0]
	v_mfma_scale_f32_16x16x128_f8f6f4 v[12:15], v[148:155], v[164:171], v[216:219], v146, v146 op_sel_hi:[0,0,0]
	v_mfma_scale_f32_16x16x128_f8f6f4 v[32:35], v[130:137], v[164:171], v[220:223], v146, v146 op_sel_hi:[0,0,0]
	v_mfma_scale_f32_16x16x128_f8f6f4 v[8:11], v[156:163], v[164:171], v[224:227], v146, v146 op_sel_hi:[0,0,0]
	v_mfma_scale_f32_16x16x128_f8f6f4 v[24:27], v[0:7], v[172:179], v[228:231], v146, v146 op_sel_hi:[0,0,0]
	v_mfma_scale_f32_16x16x128_f8f6f4 v[4:7], v[148:155], v[172:179], v[232:235], v146, v146 op_sel_hi:[0,0,0]
	v_mfma_scale_f32_16x16x128_f8f6f4 v[16:19], v[130:137], v[172:179], v[236:239], v146, v146 op_sel_hi:[0,0,0]
	v_mfma_scale_f32_16x16x128_f8f6f4 v[0:3], v[156:163], v[172:179], v[240:243], v146, v146 op_sel_hi:[0,0,0]
	s_setprio 0
	s_barrier
	s_add_u32 s52, s52, 0x100
	s_addc_u32 s53, s53, 0
	s_add_u32 s21, s21, 0x100
	s_addc_u32 s24, s24, 0
	s_cmp_ge_i32 s30, s22
	s_mov_b32 s31, s30
	s_cbranch_scc0 .LBB0_239
	v_pk_mul_f32 v[126:127], v[126:127], s[42:43] op_sel_hi:[1,0]
	v_pk_mul_f32 v[124:125], v[124:125], s[42:43] op_sel_hi:[1,0]
	v_pk_mul_f32 v[122:123], v[122:123], s[42:43] op_sel_hi:[1,0]
	v_pk_mul_f32 v[120:121], v[120:121], s[42:43] op_sel_hi:[1,0]
	v_pk_mul_f32 v[130:131], v[110:111], s[42:43] op_sel_hi:[1,0]
	v_pk_mul_f32 v[132:133], v[108:109], s[42:43] op_sel_hi:[1,0]
	v_pk_mul_f32 v[134:135], v[102:103], s[42:43] op_sel_hi:[1,0]
	v_pk_mul_f32 v[136:137], v[100:101], s[42:43] op_sel_hi:[1,0]
	v_pk_mul_f32 v[100:101], v[118:119], s[42:43] op_sel_hi:[1,0]
	v_pk_mul_f32 v[102:103], v[116:117], s[42:43] op_sel_hi:[1,0]
	v_pk_mul_f32 v[108:109], v[114:115], s[42:43] op_sel_hi:[1,0]
	v_pk_mul_f32 v[110:111], v[112:113], s[42:43] op_sel_hi:[1,0]
	v_pk_mul_f32 v[112:113], v[94:95], s[42:43] op_sel_hi:[1,0]
	v_pk_mul_f32 v[114:115], v[92:93], s[42:43] op_sel_hi:[1,0]
	v_pk_mul_f32 v[116:117], v[86:87], s[42:43] op_sel_hi:[1,0]
	v_pk_mul_f32 v[118:119], v[84:85], s[42:43] op_sel_hi:[1,0]
	v_pk_mul_f32 v[84:85], v[106:107], s[42:43] op_sel_hi:[1,0]
	v_pk_mul_f32 v[86:87], v[104:105], s[42:43] op_sel_hi:[1,0]
	v_pk_mul_f32 v[92:93], v[98:99], s[42:43] op_sel_hi:[1,0]
	v_pk_mul_f32 v[94:95], v[96:97], s[42:43] op_sel_hi:[1,0]
	v_pk_mul_f32 v[96:97], v[78:79], s[42:43] op_sel_hi:[1,0]
	v_pk_mul_f32 v[98:99], v[76:77], s[42:43] op_sel_hi:[1,0]
	v_pk_mul_f32 v[104:105], v[74:75], s[42:43] op_sel_hi:[1,0]
	v_pk_mul_f32 v[106:107], v[72:73], s[42:43] op_sel_hi:[1,0]
	v_pk_mul_f32 v[72:73], v[90:91], s[42:43] op_sel_hi:[1,0]
	v_pk_mul_f32 v[74:75], v[88:89], s[42:43] op_sel_hi:[1,0]
	v_pk_mul_f32 v[76:77], v[82:83], s[42:43] op_sel_hi:[1,0]
	v_pk_mul_f32 v[78:79], v[80:81], s[42:43] op_sel_hi:[1,0]
	v_pk_mul_f32 v[70:71], v[70:71], s[42:43] op_sel_hi:[1,0]
	v_pk_mul_f32 v[68:69], v[68:69], s[42:43] op_sel_hi:[1,0]
	v_pk_mul_f32 v[62:63], v[62:63], s[42:43] op_sel_hi:[1,0]
	v_pk_mul_f32 v[80:81], v[60:61], s[42:43] op_sel_hi:[1,0]
	v_pk_mul_f32 v[60:61], v[66:67], s[42:43] op_sel_hi:[1,0]
	v_pk_mul_f32 v[64:65], v[64:65], s[42:43] op_sel_hi:[1,0]
	v_pk_mul_f32 v[58:59], v[58:59], s[42:43] op_sel_hi:[1,0]
	v_pk_mul_f32 v[56:57], v[56:57], s[42:43] op_sel_hi:[1,0]
	v_pk_mul_f32 v[66:67], v[46:47], s[42:43] op_sel_hi:[1,0]
	v_pk_mul_f32 v[82:83], v[44:45], s[42:43] op_sel_hi:[1,0]
	v_pk_mul_f32 v[88:89], v[38:39], s[42:43] op_sel_hi:[1,0]
	v_pk_mul_f32 v[90:91], v[36:37], s[42:43] op_sel_hi:[1,0]
	v_pk_mul_f32 v[36:37], v[54:55], s[42:43] op_sel_hi:[1,0]
	v_pk_mul_f32 v[38:39], v[52:53], s[42:43] op_sel_hi:[1,0]
	v_pk_mul_f32 v[44:45], v[50:51], s[42:43] op_sel_hi:[1,0]
	v_pk_mul_f32 v[46:47], v[48:49], s[42:43] op_sel_hi:[1,0]
	v_pk_mul_f32 v[48:49], v[30:31], s[42:43] op_sel_hi:[1,0]
	v_pk_mul_f32 v[50:51], v[28:29], s[42:43] op_sel_hi:[1,0]
	v_pk_mul_f32 v[52:53], v[22:23], s[42:43] op_sel_hi:[1,0]
	v_pk_mul_f32 v[54:55], v[20:21], s[42:43] op_sel_hi:[1,0]
	v_pk_mul_f32 v[20:21], v[42:43], s[42:43] op_sel_hi:[1,0]
	v_pk_mul_f32 v[22:23], v[40:41], s[42:43] op_sel_hi:[1,0]
	v_pk_mul_f32 v[28:29], v[34:35], s[42:43] op_sel_hi:[1,0]
	v_pk_mul_f32 v[30:31], v[32:33], s[42:43] op_sel_hi:[1,0]
	v_pk_mul_f32 v[32:33], v[14:15], s[42:43] op_sel_hi:[1,0]
	v_pk_mul_f32 v[34:35], v[12:13], s[42:43] op_sel_hi:[1,0]
	v_pk_mul_f32 v[40:41], v[10:11], s[42:43] op_sel_hi:[1,0]
	v_pk_mul_f32 v[42:43], v[8:9], s[42:43] op_sel_hi:[1,0]
	v_pk_mul_f32 v[8:9], v[26:27], s[42:43] op_sel_hi:[1,0]
	v_pk_mul_f32 v[10:11], v[24:25], s[42:43] op_sel_hi:[1,0]
	v_pk_mul_f32 v[12:13], v[18:19], s[42:43] op_sel_hi:[1,0]
	v_pk_mul_f32 v[14:15], v[16:17], s[42:43] op_sel_hi:[1,0]
	v_pk_mul_f32 v[6:7], v[6:7], s[42:43] op_sel_hi:[1,0]
	v_pk_mul_f32 v[4:5], v[4:5], s[42:43] op_sel_hi:[1,0]
	v_pk_mul_f32 v[2:3], v[2:3], s[42:43] op_sel_hi:[1,0]
	v_pk_mul_f32 v[0:1], v[0:1], s[42:43] op_sel_hi:[1,0]
	s_and_b64 vcc, exec, s[96:97]
	s_cbranch_vccz .LBB0_242

; #define PG8_LDA(dst, b, h) do { if constexpr (FP8) { _Pragma("unroll") for (int m = 0; m < 4; ++m) dst##8[m] = PG8_LD8(PG8_SA(b, h), aoff, aoff1, m); } \
;         else { _Pragma("unroll") for (int m = 0; m < 4; ++m) _Pragma("unroll") for (int k = 0; k < 2; ++k) dst[m][k] = *(const LAS bf16x8*)(lds + PG8_SA(b, h) + (k ? aoff1 : aoff) + m * 2048); } } while (0)
; #define PG8_LDB(dst, b, h) do { if constexpr (FP8) { dst##8[0] = PG8_LD8(PG8_SB(b, h), boff, boff1, 0); dst##8[1] = PG8_LD8(PG8_SB(b, h), boff, boff1, 1); } \
;         else { _Pragma("unroll") for (int n = 0; n < 2; ++n) _Pragma("unroll") for (int k = 0; k < 2; ++k) dst[n][k] = *(const LAS bf16x8*)(lds + PG8_SB(b, h) + (k ? boff1 : boff) + n * 2048); } } while (0)
; #define PG8_WAIT_V(n) asm volatile("s_waitcnt vmcnt(" #n ")" ::: "memory")
; #define PG8_WAIT_L(n) asm volatile("s_waitcnt lgkmcnt(" #n ")" ::: "memory")
; #define PG8_BAR __builtin_amdgcn_s_barrier()
; #define PG8_SCHED __builtin_amdgcn_sched_barrier(0)
; #define PG8_S1 PG8_STAGE(PG8_SA(1, 1), a1 + hstepA, voffA)
; #define PG8_S2 do { PG8_STAGE(PG8_SB(0, 0), b2, voffB); PG8_STAGE(PG8_SB(0, 1), b2 + hstepB, voffB); PG8_STAGE(PG8_SA(0, 0), a2, voffA); } while (0)
; template <class Epi, class SchedT, bool ALIGN_EPI, bool SP2, bool FP8 = false>
; __device__ __forceinline__ void gemm_phase(LAS unsigned char* lds, const Gemm g, const SchedT& S, const Epi& E, const int wid) {
;     ...
;         for (int t = 0; t < nt; t += 2) {
;             const bool last = (t == nt - 2);
;             const char* a1 = cA + (size_t)(t + 1) * kstep;
;             const char* a2 = last ? nA : cA + (size_t)(t + 2) * kstep; const char* b2 = last ? nB : cB + (size_t)(t + 2) * kstep;
;             const char* a3 = a2 + kstep; const char* b3 = b2 + kstep;
;             if constexpr (SP2) {
;     ...
;             PG8_LDB(B0, 0, 0); PG8_LDB(B1, 0, 1); PG8_SCHED; PG8_LDA(At, 0, 0); PG8_S1;
;             PG8_WAIT_V(8); PG8_WAIT_L(0); PG8_BAR; PG8_MMAP(0, 0, 0); PG8_BAR; PG8_SCHED;
;             PG8_LDA(At, 0, 1); PG8_S2;
;             PG8_WAIT_V(8); PG8_WAIT_L(0); PG8_BAR; PG8_MMAP(1, 0, 1); PG8_BAR; PG8_SCHED;
.LBB0_539:
	ds_read_b128 v[134:137], v215
	ds_read_b128 v[138:141], v215 offset:16
	ds_read_b128 v[142:145], v215 offset:2048
	ds_read_b128 v[146:149], v215 offset:2064
	ds_read_b128 v[150:153], v216
	ds_read_b128 v[154:157], v216 offset:16
	ds_read_b128 v[158:161], v216 offset:2048
	ds_read_b128 v[162:165], v216 offset:2064
	s_add_i32 s30, s10, 2
	s_add_u32 s16, s8, 0xfff70080
	s_addc_u32 s11, s9, -1
	s_cmp_eq_u32 s20, s10
	s_cselect_b32 s10, s52, s16
	s_cselect_b32 s11, s53, s11
	v_mov_b32_e32 v128, v210
	ds_read_b128 v[166:169], v217
	ds_read_b128 v[170:173], v217 offset:16
	ds_read_b128 v[174:177], v217 offset:2048
	ds_read_b128 v[178:181], v217 offset:2064
	ds_read_b128 v[182:185], v217 offset:4096
	ds_read_b128 v[186:189], v217 offset:4112
	ds_read_b128 v[190:193], v217 offset:6144
	ds_read_b128 v[194:197], v217 offset:6160
	s_cselect_b32 s67, s65, s24
	s_cselect_b32 s66, s64, s21
	s_add_i32 m0, s87, 0xc000
	s_nop 0
	global_load_lds_dwordx4 v128, s[8:9]
	v_mov_b32_e32 v128, v212
	s_add_i32 m0, s87, 0xe000
	s_nop 0
	global_load_lds_dwordx4 v128, s[8:9]
	s_waitcnt vmcnt(8)
	s_waitcnt lgkmcnt(0)
	s_barrier
	s_setprio 1
	s_waitcnt lgkmcnt(0)
	v_mfma_scale_f32_16x16x128_f8f6f4 v[124:127], v[134:141], v[166:173], v[124:127], v218, v218 op_sel_hi:[0,0,0]
	v_mfma_scale_f32_16x16x128_f8f6f4 v[120:123], v[142:149], v[166:173], v[120:123], v218, v218 op_sel_hi:[0,0,0]
	v_mfma_scale_f32_16x16x128_f8f6f4 v[116:119], v[134:141], v[174:181], v[116:119], v218, v218 op_sel_hi:[0,0,0]
	v_mfma_scale_f32_16x16x128_f8f6f4 v[112:115], v[142:149], v[174:181], v[112:115], v218, v218 op_sel_hi:[0,0,0]
	v_mfma_scale_f32_16x16x128_f8f6f4 v[108:111], v[134:141], v[182:189], v[108:111], v218, v218 op_sel_hi:[0,0,0]
	v_mfma_scale_f32_16x16x128_f8f6f4 v[104:107], v[142:149], v[182:189], v[104:107], v218, v218 op_sel_hi:[0,0,0]
	v_mfma_scale_f32_16x16x128_f8f6f4 v[100:103], v[134:141], v[190:197], v[100:103], v218, v218 op_sel_hi:[0,0,0]
	v_mfma_scale_f32_16x16x128_f8f6f4 v[96:99], v[142:149], v[190:197], v[96:99], v218, v218 op_sel_hi:[0,0,0]
	s_setprio 0
	s_setprio 1
	v_mfma_scale_f32_16x16x128_f8f6f4 v[198:201], v[150:157], v[166:173], v[92:95], v218, v218 op_sel_hi:[0,0,0]
	v_mfma_scale_f32_16x16x128_f8f6f4 v[166:169], v[158:165], v[166:173], v[88:91], v218, v218 op_sel_hi:[0,0,0]
	v_mfma_scale_f32_16x16x128_f8f6f4 v[170:173], v[150:157], v[174:181], v[84:87], v218, v218 op_sel_hi:[0,0,0]
	v_mfma_scale_f32_16x16x128_f8f6f4 v[174:177], v[158:165], v[174:181], v[80:83], v218, v218 op_sel_hi:[0,0,0]
	v_mfma_scale_f32_16x16x128_f8f6f4 v[178:181], v[150:157], v[182:189], v[76:79], v218, v218 op_sel_hi:[0,0,0]
	v_mfma_scale_f32_16x16x128_f8f6f4 v[182:185], v[158:165], v[182:189], v[72:75], v218, v218 op_sel_hi:[0,0,0]
	v_mfma_scale_f32_16x16x128_f8f6f4 v[186:189], v[150:157], v[190:197], v[68:71], v218, v218 op_sel_hi:[0,0,0]
	v_mfma_scale_f32_16x16x128_f8f6f4 v[190:193], v[158:165], v[190:197], v[64:67], v218, v218 op_sel_hi:[0,0,0]
	s_setprio 0
	s_barrier
	v_mov_b32_e32 v128, v211
	s_add_i32 s16, s94, s86
	s_nop 2
	ds_read_b128 v[64:67], v217 offset:16384
	ds_read_b128 v[68:71], v217 offset:16400
	ds_read_b128 v[72:75], v217 offset:18432
	ds_read_b128 v[76:79], v217 offset:18448
	ds_read_b128 v[80:83], v217 offset:20480
	ds_read_b128 v[84:87], v217 offset:20496
	ds_read_b128 v[88:91], v217 offset:22528
	ds_read_b128 v[92:95], v217 offset:22544
	s_mov_b32 m0, s16
	s_nop 0
	global_load_lds_dwordx4 v128, s[66:67]
	v_mov_b32_e32 v128, v213
	s_add_i32 m0, s16, 0x2000
	s_add_u32 s60, s66, 0x88000
	global_load_lds_dwordx4 v128, s[66:67]
	s_addc_u32 s61, s67, 0
	v_mov_b32_e32 v128, v211
	s_add_i32 s16, s95, s86
	s_mov_b32 m0, s16
	s_nop 0
	global_load_lds_dwordx4 v128, s[60:61]
	v_mov_b32_e32 v128, v213
	s_add_i32 m0, s16, 0x2000
	s_nop 0
	global_load_lds_dwordx4 v128, s[60:61]
	v_mov_b32_e32 v128, v210
	s_mov_b32 m0, s87
	s_nop 0
	global_load_lds_dwordx4 v128, s[10:11]
	v_mov_b32_e32 v128, v212
	s_mov_b32 m0, s88
	s_nop 0
	global_load_lds_dwordx4 v128, s[10:11]
	s_waitcnt vmcnt(8)
	s_waitcnt lgkmcnt(0)
	s_barrier
	s_setprio 1
	s_waitcnt lgkmcnt(0)
	v_mfma_scale_f32_16x16x128_f8f6f4 v[60:63], v[134:141], v[64:71], v[60:63], v218, v218 op_sel_hi:[0,0,0]
	v_mfma_scale_f32_16x16x128_f8f6f4 v[56:59], v[142:149], v[64:71], v[56:59], v218, v218 op_sel_hi:[0,0,0]
	v_mfma_scale_f32_16x16x128_f8f6f4 v[52:55], v[134:141], v[72:79], v[52:55], v218, v218 op_sel_hi:[0,0,0]
	v_mfma_scale_f32_16x16x128_f8f6f4 v[48:51], v[142:149], v[72:79], v[48:51], v218, v218 op_sel_hi:[0,0,0]
	v_mfma_scale_f32_16x16x128_f8f6f4 v[44:47], v[134:141], v[80:87], v[44:47], v218, v218 op_sel_hi:[0,0,0]
	v_mfma_scale_f32_16x16x128_f8f6f4 v[40:43], v[142:149], v[80:87], v[40:43], v218, v218 op_sel_hi:[0,0,0]
	v_mfma_scale_f32_16x16x128_f8f6f4 v[194:197], v[150:157], v[64:71], v[28:31], v218, v218 op_sel_hi:[0,0,0]
	v_mfma_scale_f32_16x16x128_f8f6f4 v[202:205], v[158:165], v[64:71], v[24:27], v218, v218 op_sel_hi:[0,0,0]
	s_setprio 0
	s_setprio 1
	v_mfma_scale_f32_16x16x128_f8f6f4 v[206:209], v[150:157], v[72:79], v[20:23], v218, v218 op_sel_hi:[0,0,0]
	v_mfma_scale_f32_16x16x128_f8f6f4 v[220:223], v[158:165], v[72:79], v[16:19], v218, v218 op_sel_hi:[0,0,0]
	v_mfma_scale_f32_16x16x128_f8f6f4 v[224:227], v[150:157], v[80:87], v[12:15], v218, v218 op_sel_hi:[0,0,0]
	v_mfma_scale_f32_16x16x128_f8f6f4 v[228:231], v[158:165], v[80:87], v[8:11], v218, v218 op_sel_hi:[0,0,0]
	v_mfma_scale_f32_16x16x128_f8f6f4 v[232:235], v[134:141], v[88:95], v[36:39], v218, v218 op_sel_hi:[0,0,0]
	v_mfma_scale_f32_16x16x128_f8f6f4 v[236:239], v[150:157], v[88:95], v[4:7], v218, v218 op_sel_hi:[0,0,0]
	v_mfma_scale_f32_16x16x128_f8f6f4 v[240:243], v[142:149], v[88:95], v[32:35], v218, v218 op_sel_hi:[0,0,0]
	v_mfma_scale_f32_16x16x128_f8f6f4 v[244:247], v[158:165], v[88:95], v[0:3], v218, v218 op_sel_hi:[0,0,0]
	s_setprio 0
	s_barrier
; #define PG8_STAGE(bufoff, gbase, voff) do { _Pragma("unroll") for (int _i = 0; _i < 2; ++_i) { unsigned vo_ = (voff)[_i]; asm volatile("" : "+v"(vo_));     \
;         __builtin_amdgcn_global_load_lds((const unsigned*)((const char*)(gbase) + vo_), (LAS unsigned*)(lds + (bufoff) + ldsw + _i * 8192), 16, 0, 0); } } while (0)
; #define PG8_WAIT_V(n) asm volatile("s_waitcnt vmcnt(" #n ")" ::: "memory")
; #define PG8_WAIT_L(n) asm volatile("s_waitcnt lgkmcnt(" #n ")" ::: "memory")
; template <class Epi, class SchedT, bool ALIGN_EPI, bool SP2, bool FP8 = false>
; __device__ __forceinline__ void gemm_phase(LAS unsigned char* lds, const Gemm g, const SchedT& S, const Epi& E, const int wid) {
;     ...
;             PG8_LDB(B0, 1, 0); PG8_LDB(B1, 1, 1); PG8_SCHED; PG8_LDA(At, 1, 0); PG8_S3;
;             PG8_WAIT_V(8); PG8_WAIT_L(0); PG8_BAR; PG8_MMAP(0, 1, 0); PG8_BAR; PG8_SCHED;
;             PG8_LDA(At, 1, 1); PG8_S4;
;             PG8_WAIT_V(8); PG8_WAIT_L(0); PG8_BAR; PG8_MMAP(1, 1, 1); PG8_BAR; PG8_SCHED;
;             } else {
;             PG8_LDB(B0, 0, 0); PG8_SCHED; PG8_LDA(At, 0, 0); PG8_STAGE(PG8_SA(1, 1), a1 + hstepA, voffA);
;             PG8_WAIT_L(8); PG8_BAR; PG8_WAIT_L(0); PG8_MMA(0, 0, At, B0); PG8_BAR; PG8_SCHED;
;             PG8_LDB(B1, 0, 1); PG8_STAGE(PG8_SB(0, 0), b2, voffB);
;             PG8_BAR; PG8_WAIT_L(0); PG8_MMA(0, 1, At, B1); PG8_BAR;
;             PG8_LDA(At, 0, 1); PG8_STAGE(PG8_SA(0, 0), a2, voffA);
;             PG8_BAR; PG8_WAIT_L(0); PG8_MMA(1, 0, At, B0); PG8_BAR; PG8_SCHED;
;             PG8_STAGE(PG8_SB(0, 1), b2 + hstepB, voffB);
;             PG8_WAIT_V(6); PG8_BAR; PG8_MMA(1, 1, At, B1); PG8_BAR;
;             PG8_LDB(B0, 1, 0); PG8_SCHED; PG8_LDA(At, 1, 0); PG8_STAGE(PG8_SA(0, 1), a2 + hstepA, voffA);
;             PG8_WAIT_L(8); PG8_BAR; PG8_WAIT_L(0); PG8_MMA(0, 0, At, B0); PG8_BAR; PG8_SCHED;
;             PG8_LDB(B1, 1, 1); PG8_STAGE(PG8_SB(1, 0), b3, voffB);
;             PG8_BAR; PG8_WAIT_L(0); PG8_MMA(0, 1, At, B1); PG8_BAR;
;             PG8_LDA(At, 1, 1); PG8_STAGE(PG8_SA(1, 0), a3, voffA);
;             PG8_BAR; PG8_WAIT_L(0); PG8_MMA(1, 0, At, B0); PG8_BAR; PG8_SCHED;
;             PG8_STAGE(PG8_SB(1, 1), b3 + hstepB, voffB);
;             PG8_WAIT_V(6); PG8_BAR; PG8_MMA(1, 1, At, B1); PG8_BAR;
;             }
;         }
;         if constexpr (ALIGN_EPI) { if (wr == 0) PG8_BAR; }
	s_add_i32 s16, 0, 0x18000
	v_add_u32_e32 v8, s16, v214
	s_add_i32 s17, 0, 0x1c000
	s_nop 1
	ds_read_b128 v[0:3], v8
	ds_read_b128 v[4:7], v8 offset:16
	ds_read_b128 v[134:137], v8 offset:2048
	ds_read_b128 v[138:141], v8 offset:2064
	v_add_u32_e32 v8, s17, v214
	ds_read_b128 v[142:145], v8
	ds_read_b128 v[146:149], v8 offset:16
	ds_read_b128 v[150:153], v8 offset:2048
	ds_read_b128 v[154:157], v8 offset:2064
	s_add_u32 s60, s10, 0x90000
	v_mov_b32_e32 v64, v210
	s_mov_b32 m0, s89
	ds_read_b128 v[8:11], v217 offset:32768
	ds_read_b128 v[12:15], v217 offset:32784
	ds_read_b128 v[16:19], v217 offset:34816
	ds_read_b128 v[20:23], v217 offset:34832
	ds_read_b128 v[24:27], v217 offset:36864
	ds_read_b128 v[28:31], v217 offset:36880
	ds_read_b128 v[32:35], v217 offset:38912
	ds_read_b128 v[36:39], v217 offset:38928
	s_addc_u32 s61, s11, 0
	s_nop 0
	global_load_lds_dwordx4 v64, s[60:61]
	v_mov_b32_e32 v64, v212
	s_mov_b32 m0, s90
	s_nop 0
	global_load_lds_dwordx4 v64, s[60:61]
	s_waitcnt vmcnt(8)
	s_waitcnt lgkmcnt(0)
	s_barrier
	s_setprio 1
	s_waitcnt lgkmcnt(0)
	v_mfma_scale_f32_16x16x128_f8f6f4 v[124:127], v[0:7], v[8:15], v[124:127], v218, v218 op_sel_hi:[0,0,0]
	v_mfma_scale_f32_16x16x128_f8f6f4 v[92:95], v[142:149], v[8:15], v[198:201], v218, v218 op_sel_hi:[0,0,0]
	v_mfma_scale_f32_16x16x128_f8f6f4 v[120:123], v[134:141], v[8:15], v[120:123], v218, v218 op_sel_hi:[0,0,0]
	v_mfma_scale_f32_16x16x128_f8f6f4 v[88:91], v[150:157], v[8:15], v[166:169], v218, v218 op_sel_hi:[0,0,0]
	v_mfma_scale_f32_16x16x128_f8f6f4 v[116:119], v[0:7], v[16:23], v[116:119], v218, v218 op_sel_hi:[0,0,0]
	v_mfma_scale_f32_16x16x128_f8f6f4 v[84:87], v[142:149], v[16:23], v[170:173], v218, v218 op_sel_hi:[0,0,0]
	v_mfma_scale_f32_16x16x128_f8f6f4 v[112:115], v[134:141], v[16:23], v[112:115], v218, v218 op_sel_hi:[0,0,0]
	v_mfma_scale_f32_16x16x128_f8f6f4 v[80:83], v[150:157], v[16:23], v[174:177], v218, v218 op_sel_hi:[0,0,0]
	s_setprio 0
	s_setprio 1
	v_mfma_scale_f32_16x16x128_f8f6f4 v[108:111], v[0:7], v[24:31], v[108:111], v218, v218 op_sel_hi:[0,0,0]
	v_mfma_scale_f32_16x16x128_f8f6f4 v[76:79], v[142:149], v[24:31], v[178:181], v218, v218 op_sel_hi:[0,0,0]
	v_mfma_scale_f32_16x16x128_f8f6f4 v[104:107], v[134:141], v[24:31], v[104:107], v218, v218 op_sel_hi:[0,0,0]
	v_mfma_scale_f32_16x16x128_f8f6f4 v[72:75], v[150:157], v[24:31], v[182:185], v218, v218 op_sel_hi:[0,0,0]
	v_mfma_scale_f32_16x16x128_f8f6f4 v[100:103], v[0:7], v[32:39], v[100:103], v218, v218 op_sel_hi:[0,0,0]
	v_mfma_scale_f32_16x16x128_f8f6f4 v[68:71], v[142:149], v[32:39], v[186:189], v218, v218 op_sel_hi:[0,0,0]
	v_mfma_scale_f32_16x16x128_f8f6f4 v[96:99], v[134:141], v[32:39], v[96:99], v218, v218 op_sel_hi:[0,0,0]
	v_mfma_scale_f32_16x16x128_f8f6f4 v[64:67], v[150:157], v[32:39], v[190:193], v218, v218 op_sel_hi:[0,0,0]
	s_setprio 0
	s_barrier
	v_mov_b32_e32 v128, v211
	ds_read_b128 v[8:11], v217 offset:49152
	ds_read_b128 v[12:15], v217 offset:49168
	ds_read_b128 v[32:35], v217 offset:51200
	ds_read_b128 v[36:39], v217 offset:51216
	ds_read_b128 v[158:161], v217 offset:53248
	ds_read_b128 v[162:165], v217 offset:53264
	ds_read_b128 v[166:169], v217 offset:55296
	ds_read_b128 v[170:173], v217 offset:55312
	s_add_i32 s16, s16, s86
	v_lshl_add_u64 v[16:17], s[66:67], 0, v[128:129]
	v_lshl_add_u64 v[16:17], v[16:17], 0, s[44:45]
	s_mov_b32 m0, s16
	v_mov_b32_e32 v128, v213
	global_load_lds_dwordx4 v[16:17], off
	s_add_i32 m0, s16, 0x2000
	v_lshl_add_u64 v[16:17], s[66:67], 0, v[128:129]
	v_lshl_add_u64 v[16:17], v[16:17], 0, s[44:45]
	s_add_u32 s60, s66, 0x88080
	global_load_lds_dwordx4 v[16:17], off
	s_addc_u32 s61, s67, 0
	v_mov_b32_e32 v16, v211
	s_add_i32 s16, s17, s86
	s_mov_b32 m0, s16
	v_mov_b32_e32 v128, v210
	global_load_lds_dwordx4 v16, s[60:61]
	v_mov_b32_e32 v16, v213
	s_add_i32 m0, s16, 0x2000
	s_nop 0
	global_load_lds_dwordx4 v16, s[60:61]
	s_mov_b32 m0, s92
	v_lshl_add_u64 v[16:17], s[10:11], 0, v[128:129]
	v_lshl_add_u64 v[16:17], v[16:17], 0, s[44:45]
	v_mov_b32_e32 v128, v212
	global_load_lds_dwordx4 v[16:17], off
	s_mov_b32 m0, s93
	v_lshl_add_u64 v[16:17], s[10:11], 0, v[128:129]
	v_lshl_add_u64 v[16:17], v[16:17], 0, s[44:45]
	global_load_lds_dwordx4 v[16:17], off
	s_waitcnt vmcnt(8)
	s_waitcnt lgkmcnt(0)
	s_barrier
	s_setprio 1
	s_waitcnt lgkmcnt(0)
	v_mfma_scale_f32_16x16x128_f8f6f4 v[60:63], v[0:7], v[8:15], v[60:63], v218, v218 op_sel_hi:[0,0,0]
	v_mfma_scale_f32_16x16x128_f8f6f4 v[28:31], v[142:149], v[8:15], v[194:197], v218, v218 op_sel_hi:[0,0,0]
	v_mfma_scale_f32_16x16x128_f8f6f4 v[56:59], v[134:141], v[8:15], v[56:59], v218, v218 op_sel_hi:[0,0,0]
	v_mfma_scale_f32_16x16x128_f8f6f4 v[24:27], v[150:157], v[8:15], v[202:205], v218, v218 op_sel_hi:[0,0,0]
	v_mfma_scale_f32_16x16x128_f8f6f4 v[52:55], v[0:7], v[32:39], v[52:55], v218, v218 op_sel_hi:[0,0,0]
	v_mfma_scale_f32_16x16x128_f8f6f4 v[20:23], v[142:149], v[32:39], v[206:209], v218, v218 op_sel_hi:[0,0,0]
	v_mfma_scale_f32_16x16x128_f8f6f4 v[48:51], v[134:141], v[32:39], v[48:51], v218, v218 op_sel_hi:[0,0,0]
	v_mfma_scale_f32_16x16x128_f8f6f4 v[16:19], v[150:157], v[32:39], v[220:223], v218, v218 op_sel_hi:[0,0,0]
	s_setprio 0
	s_setprio 1
	v_mfma_scale_f32_16x16x128_f8f6f4 v[44:47], v[0:7], v[158:165], v[44:47], v218, v218 op_sel_hi:[0,0,0]
	v_mfma_scale_f32_16x16x128_f8f6f4 v[12:15], v[142:149], v[158:165], v[224:227], v218, v218 op_sel_hi:[0,0,0]
	v_mfma_scale_f32_16x16x128_f8f6f4 v[40:43], v[134:141], v[158:165], v[40:43], v218, v218 op_sel_hi:[0,0,0]
	v_mfma_scale_f32_16x16x128_f8f6f4 v[8:11], v[150:157], v[158:165], v[228:231], v218, v218 op_sel_hi:[0,0,0]
	v_mfma_scale_f32_16x16x128_f8f6f4 v[36:39], v[0:7], v[166:173], v[232:235], v218, v218 op_sel_hi:[0,0,0]
	v_mfma_scale_f32_16x16x128_f8f6f4 v[4:7], v[142:149], v[166:173], v[236:239], v218, v218 op_sel_hi:[0,0,0]
	v_mfma_scale_f32_16x16x128_f8f6f4 v[32:35], v[134:141], v[166:173], v[240:243], v218, v218 op_sel_hi:[0,0,0]
	v_mfma_scale_f32_16x16x128_f8f6f4 v[0:3], v[150:157], v[166:173], v[244:247], v218, v218 op_sel_hi:[0,0,0]
	s_setprio 0
	s_barrier
	s_add_u32 s8, s8, 0x100
	s_addc_u32 s9, s9, 0
	s_add_u32 s21, s21, 0x100
	s_addc_u32 s24, s24, 0
	s_cmp_ge_i32 s30, s71
	s_mov_b32 s10, s30
	s_cbranch_scc0 .LBB0_539
	s_and_b64 vcc, exec, s[96:97]
	s_cbranch_vccz .LBB0_542

; #define PG8_LDA(dst, b, h) do { if constexpr (FP8) { _Pragma("unroll") for (int m = 0; m < 4; ++m) dst##8[m] = PG8_LD8(PG8_SA(b, h), aoff, aoff1, m); } \
;         else { _Pragma("unroll") for (int m = 0; m < 4; ++m) _Pragma("unroll") for (int k = 0; k < 2; ++k) dst[m][k] = *(const LAS bf16x8*)(lds + PG8_SA(b, h) + (k ? aoff1 : aoff) + m * 2048); } } while (0)
; #define PG8_LDB(dst, b, h) do { if constexpr (FP8) { dst##8[0] = PG8_LD8(PG8_SB(b, h), boff, boff1, 0); dst##8[1] = PG8_LD8(PG8_SB(b, h), boff, boff1, 1); } \
;         else { _Pragma("unroll") for (int n = 0; n < 2; ++n) _Pragma("unroll") for (int k = 0; k < 2; ++k) dst[n][k] = *(const LAS bf16x8*)(lds + PG8_SB(b, h) + (k ? boff1 : boff) + n * 2048); } } while (0)
; #define PG8_WAIT_V(n) asm volatile("s_waitcnt vmcnt(" #n ")" ::: "memory")
; #define PG8_WAIT_L(n) asm volatile("s_waitcnt lgkmcnt(" #n ")" ::: "memory")
; #define PG8_BAR __builtin_amdgcn_s_barrier()
; #define PG8_SCHED __builtin_amdgcn_sched_barrier(0)
; #define PG8_S1 PG8_STAGE(PG8_SA(1, 1), a1 + hstepA, voffA)
; #define PG8_S2 do { PG8_STAGE(PG8_SB(0, 0), b2, voffB); PG8_STAGE(PG8_SB(0, 1), b2 + hstepB, voffB); PG8_STAGE(PG8_SA(0, 0), a2, voffA); } while (0)
; template <class Epi, class SchedT, bool ALIGN_EPI, bool SP2, bool FP8 = false>
; __device__ __forceinline__ void gemm_phase(LAS unsigned char* lds, const Gemm g, const SchedT& S, const Epi& E, const int wid) {
;     ...
;         for (int t = 0; t < nt; t += 2) {
;             const bool last = (t == nt - 2);
;             const char* a1 = cA + (size_t)(t + 1) * kstep;
;             const char* a2 = last ? nA : cA + (size_t)(t + 2) * kstep; const char* b2 = last ? nB : cB + (size_t)(t + 2) * kstep;
;             const char* a3 = a2 + kstep; const char* b3 = b2 + kstep;
;             if constexpr (SP2) {
;     ...
;             PG8_LDB(B0, 0, 0); PG8_LDB(B1, 0, 1); PG8_SCHED; PG8_LDA(At, 0, 0); PG8_S1;
;             PG8_WAIT_V(8); PG8_WAIT_L(0); PG8_BAR; PG8_MMAP(0, 0, 0); PG8_BAR; PG8_SCHED;
;             PG8_LDA(At, 0, 1); PG8_S2;
;             PG8_WAIT_V(8); PG8_WAIT_L(0); PG8_BAR; PG8_MMAP(1, 0, 1); PG8_BAR; PG8_SCHED;
.LBB0_779:
	ds_read_b128 v[134:137], v149
	ds_read_b128 v[138:141], v149 offset:16
	ds_read_b128 v[154:157], v149 offset:2048
	ds_read_b128 v[158:161], v149 offset:2064
	ds_read_b128 v[162:165], v150
	ds_read_b128 v[166:169], v150 offset:16
	ds_read_b128 v[170:173], v150 offset:2048
	ds_read_b128 v[174:177], v150 offset:2064
	s_add_i32 s45, s47, 2
	s_add_u32 s16, s52, 0xfffe0080
	s_addc_u32 s17, s53, -1
	s_cmp_eq_u32 s24, s47
	s_cselect_b32 s65, s9, s17
	s_cselect_b32 s64, s21, s16
	v_mov_b32_e32 v128, v146
	ds_read_b128 v[178:181], v151
	ds_read_b128 v[182:185], v151 offset:16
	ds_read_b128 v[186:189], v151 offset:2048
	ds_read_b128 v[190:193], v151 offset:2064
	ds_read_b128 v[194:197], v151 offset:4096
	ds_read_b128 v[198:201], v151 offset:4112
	ds_read_b128 v[202:205], v151 offset:6144
	ds_read_b128 v[206:209], v151 offset:6160
	s_cselect_b32 s67, s22, s31
	s_cselect_b32 s66, s23, s30
	s_add_i32 m0, s87, 0xc000
	s_nop 0
	global_load_lds_dwordx4 v128, s[52:53]
	v_mov_b32_e32 v128, v147
	s_add_i32 m0, s87, 0xe000
	s_nop 0
	global_load_lds_dwordx4 v128, s[52:53]
	s_waitcnt vmcnt(8)
	s_waitcnt lgkmcnt(0)
	s_barrier
	s_setprio 1
	s_waitcnt lgkmcnt(0)
	v_mfma_scale_f32_16x16x128_f8f6f4 v[124:127], v[134:141], v[178:185], v[124:127], v152, v152 op_sel_hi:[0,0,0]
	v_mfma_scale_f32_16x16x128_f8f6f4 v[108:111], v[162:169], v[178:185], v[108:111], v152, v152 op_sel_hi:[0,0,0]
	v_mfma_scale_f32_16x16x128_f8f6f4 v[120:123], v[154:161], v[178:185], v[120:123], v152, v152 op_sel_hi:[0,0,0]
	v_mfma_scale_f32_16x16x128_f8f6f4 v[100:103], v[170:177], v[178:185], v[100:103], v152, v152 op_sel_hi:[0,0,0]
	v_mfma_scale_f32_16x16x128_f8f6f4 v[116:119], v[134:141], v[186:193], v[116:119], v152, v152 op_sel_hi:[0,0,0]
	v_mfma_scale_f32_16x16x128_f8f6f4 v[112:115], v[154:161], v[186:193], v[112:115], v152, v152 op_sel_hi:[0,0,0]
	v_mfma_scale_f32_16x16x128_f8f6f4 v[104:107], v[134:141], v[194:201], v[104:107], v152, v152 op_sel_hi:[0,0,0]
	v_mfma_scale_f32_16x16x128_f8f6f4 v[60:63], v[170:177], v[202:209], v[60:63], v152, v152 op_sel_hi:[0,0,0]
	s_setprio 0
	s_setprio 1
	v_mfma_scale_f32_16x16x128_f8f6f4 v[142:145], v[162:169], v[186:193], v[92:95], v152, v152 op_sel_hi:[0,0,0]
	v_mfma_scale_f32_16x16x128_f8f6f4 v[178:181], v[170:177], v[186:193], v[84:87], v152, v152 op_sel_hi:[0,0,0]
	v_mfma_scale_f32_16x16x128_f8f6f4 v[182:185], v[162:169], v[194:201], v[76:79], v152, v152 op_sel_hi:[0,0,0]
	v_mfma_scale_f32_16x16x128_f8f6f4 v[186:189], v[154:161], v[194:201], v[96:99], v152, v152 op_sel_hi:[0,0,0]
	v_mfma_scale_f32_16x16x128_f8f6f4 v[190:193], v[170:177], v[194:201], v[72:75], v152, v152 op_sel_hi:[0,0,0]
	v_mfma_scale_f32_16x16x128_f8f6f4 v[194:197], v[134:141], v[202:209], v[88:91], v152, v152 op_sel_hi:[0,0,0]
	v_mfma_scale_f32_16x16x128_f8f6f4 v[198:201], v[162:169], v[202:209], v[68:71], v152, v152 op_sel_hi:[0,0,0]
	v_mfma_scale_f32_16x16x128_f8f6f4 v[210:213], v[154:161], v[202:209], v[80:83], v152, v152 op_sel_hi:[0,0,0]
	s_setprio 0
	s_barrier
	v_mov_b32_e32 v128, v146
	s_add_i32 s16, s94, s86
	s_nop 1
	ds_read_b128 v[68:71], v151 offset:16384
	ds_read_b128 v[72:75], v151 offset:16400
	ds_read_b128 v[76:79], v151 offset:18432
	ds_read_b128 v[80:83], v151 offset:18448
	ds_read_b128 v[84:87], v151 offset:20480
	ds_read_b128 v[88:91], v151 offset:20496
	ds_read_b128 v[92:95], v151 offset:22528
	ds_read_b128 v[96:99], v151 offset:22544
	s_mov_b32 m0, s16
	s_nop 0
	global_load_lds_dwordx4 v128, s[66:67]
	v_mov_b32_e32 v128, v147
	s_add_i32 m0, s16, 0x2000
	s_add_u32 s60, s66, 0x20000
	global_load_lds_dwordx4 v128, s[66:67]
	s_addc_u32 s61, s67, 0
	v_mov_b32_e32 v128, v146
	s_add_i32 s16, s95, s86
	s_mov_b32 m0, s16
	s_nop 0
	global_load_lds_dwordx4 v128, s[60:61]
	v_mov_b32_e32 v128, v147
	s_add_i32 m0, s16, 0x2000
	s_nop 0
	global_load_lds_dwordx4 v128, s[60:61]
	v_mov_b32_e32 v128, v146
	s_mov_b32 m0, s87
	s_nop 0
	global_load_lds_dwordx4 v128, s[64:65]
	v_mov_b32_e32 v128, v147
	s_mov_b32 m0, s88
	s_nop 0
	global_load_lds_dwordx4 v128, s[64:65]
	s_waitcnt vmcnt(8)
	s_waitcnt lgkmcnt(0)
	s_barrier
	s_setprio 1
	s_waitcnt lgkmcnt(0)
	v_mfma_scale_f32_16x16x128_f8f6f4 v[64:67], v[134:141], v[68:75], v[64:67], v152, v152 op_sel_hi:[0,0,0]
	v_mfma_scale_f32_16x16x128_f8f6f4 v[44:47], v[162:169], v[68:75], v[44:47], v152, v152 op_sel_hi:[0,0,0]
	v_mfma_scale_f32_16x16x128_f8f6f4 v[56:59], v[154:161], v[68:75], v[56:59], v152, v152 op_sel_hi:[0,0,0]
	v_mfma_scale_f32_16x16x128_f8f6f4 v[52:55], v[134:141], v[76:83], v[52:55], v152, v152 op_sel_hi:[0,0,0]
	v_mfma_scale_f32_16x16x128_f8f6f4 v[48:51], v[154:161], v[76:83], v[48:51], v152, v152 op_sel_hi:[0,0,0]
	v_mfma_scale_f32_16x16x128_f8f6f4 v[40:43], v[134:141], v[84:91], v[40:43], v152, v152 op_sel_hi:[0,0,0]
	v_mfma_scale_f32_16x16x128_f8f6f4 v[202:205], v[170:177], v[68:75], v[36:39], v152, v152 op_sel_hi:[0,0,0]
	v_mfma_scale_f32_16x16x128_f8f6f4 v[206:209], v[162:169], v[76:83], v[28:31], v152, v152 op_sel_hi:[0,0,0]
	s_setprio 0
	s_setprio 1
	v_mfma_scale_f32_16x16x128_f8f6f4 v[214:217], v[170:177], v[76:83], v[20:23], v152, v152 op_sel_hi:[0,0,0]
	v_mfma_scale_f32_16x16x128_f8f6f4 v[218:221], v[162:169], v[84:91], v[12:15], v152, v152 op_sel_hi:[0,0,0]
	v_mfma_scale_f32_16x16x128_f8f6f4 v[222:225], v[154:161], v[84:91], v[32:35], v152, v152 op_sel_hi:[0,0,0]
	v_mfma_scale_f32_16x16x128_f8f6f4 v[226:229], v[170:177], v[84:91], v[8:11], v152, v152 op_sel_hi:[0,0,0]
	v_mfma_scale_f32_16x16x128_f8f6f4 v[230:233], v[134:141], v[92:99], v[24:27], v152, v152 op_sel_hi:[0,0,0]
	v_mfma_scale_f32_16x16x128_f8f6f4 v[234:237], v[162:169], v[92:99], v[4:7], v152, v152 op_sel_hi:[0,0,0]
	v_mfma_scale_f32_16x16x128_f8f6f4 v[238:241], v[154:161], v[92:99], v[16:19], v152, v152 op_sel_hi:[0,0,0]
	v_mfma_scale_f32_16x16x128_f8f6f4 v[242:245], v[170:177], v[92:99], v[0:3], v152, v152 op_sel_hi:[0,0,0]
	s_setprio 0
	s_barrier
; #define PG8_LDA(dst, b, h) do { if constexpr (FP8) { _Pragma("unroll") for (int m = 0; m < 4; ++m) dst##8[m] = PG8_LD8(PG8_SA(b, h), aoff, aoff1, m); } \
;         else { _Pragma("unroll") for (int m = 0; m < 4; ++m) _Pragma("unroll") for (int k = 0; k < 2; ++k) dst[m][k] = *(const LAS bf16x8*)(lds + PG8_SA(b, h) + (k ? aoff1 : aoff) + m * 2048); } } while (0)
; #define PG8_LDB(dst, b, h) do { if constexpr (FP8) { dst##8[0] = PG8_LD8(PG8_SB(b, h), boff, boff1, 0); dst##8[1] = PG8_LD8(PG8_SB(b, h), boff, boff1, 1); } \
;         else { _Pragma("unroll") for (int n = 0; n < 2; ++n) _Pragma("unroll") for (int k = 0; k < 2; ++k) dst[n][k] = *(const LAS bf16x8*)(lds + PG8_SB(b, h) + (k ? boff1 : boff) + n * 2048); } } while (0)
; #define PG8_WAIT_V(n) asm volatile("s_waitcnt vmcnt(" #n ")" ::: "memory")
; #define PG8_WAIT_L(n) asm volatile("s_waitcnt lgkmcnt(" #n ")" ::: "memory")
; #define PG8_BAR __builtin_amdgcn_s_barrier()
; #define PG8_SCHED __builtin_amdgcn_sched_barrier(0)
; #define PG8_S3 PG8_STAGE(PG8_SA(0, 1), a2 + hstepA, voffA)
; #define PG8_S4 do { PG8_STAGE(PG8_SB(1, 0), b3, voffB); PG8_STAGE(PG8_SB(1, 1), b3 + hstepB, voffB); PG8_STAGE(PG8_SA(1, 0), a3, voffA); } while (0)
; template <class Epi, class SchedT, bool ALIGN_EPI, bool SP2, bool FP8 = false>
; __device__ __forceinline__ void gemm_phase(LAS unsigned char* lds, const Gemm g, const SchedT& S, const Epi& E, const int wid) {
;     ...
;             PG8_LDB(B0, 1, 0); PG8_LDB(B1, 1, 1); PG8_SCHED; PG8_LDA(At, 1, 0); PG8_S3;
;             PG8_WAIT_V(8); PG8_WAIT_L(0); PG8_BAR; PG8_MMAP(0, 1, 0); PG8_BAR; PG8_SCHED;
;             PG8_LDA(At, 1, 1); PG8_S4;
	s_add_i32 s16, 0, 0x18000
	v_add_u32_e32 v8, s16, v148
	s_add_i32 s17, 0, 0x1c000
	s_nop 1
	ds_read_b128 v[0:3], v8
	ds_read_b128 v[4:7], v8 offset:16
	ds_read_b128 v[134:137], v8 offset:2048
	ds_read_b128 v[138:141], v8 offset:2064
	v_add_u32_e32 v8, s17, v148
	ds_read_b128 v[154:157], v8
	ds_read_b128 v[158:161], v8 offset:16
	ds_read_b128 v[162:165], v8 offset:2048
	ds_read_b128 v[166:169], v8 offset:2064
	s_add_u32 s60, s64, 0x20000
	v_mov_b32_e32 v68, v146
	s_mov_b32 m0, s89
	ds_read_b128 v[8:11], v151 offset:32768
	ds_read_b128 v[12:15], v151 offset:32784
	ds_read_b128 v[16:19], v151 offset:34816
	ds_read_b128 v[20:23], v151 offset:34832
	ds_read_b128 v[24:27], v151 offset:36864
	ds_read_b128 v[28:31], v151 offset:36880
	ds_read_b128 v[32:35], v151 offset:38912
	ds_read_b128 v[36:39], v151 offset:38928
	s_addc_u32 s61, s65, 0
	s_nop 0
	global_load_lds_dwordx4 v68, s[60:61]
	v_mov_b32_e32 v68, v147
	s_mov_b32 m0, s90
	s_nop 0
	global_load_lds_dwordx4 v68, s[60:61]
	s_waitcnt vmcnt(8)
	s_waitcnt lgkmcnt(0)
	s_barrier
	s_setprio 1
	s_waitcnt lgkmcnt(0)
	v_mfma_scale_f32_16x16x128_f8f6f4 v[124:127], v[0:7], v[8:15], v[124:127], v152, v152 op_sel_hi:[0,0,0]
	v_mfma_scale_f32_16x16x128_f8f6f4 v[108:111], v[154:161], v[8:15], v[108:111], v152, v152 op_sel_hi:[0,0,0]
	v_mfma_scale_f32_16x16x128_f8f6f4 v[120:123], v[134:141], v[8:15], v[120:123], v152, v152 op_sel_hi:[0,0,0]
	v_mfma_scale_f32_16x16x128_f8f6f4 v[100:103], v[162:169], v[8:15], v[100:103], v152, v152 op_sel_hi:[0,0,0]
	v_mfma_scale_f32_16x16x128_f8f6f4 v[116:119], v[0:7], v[16:23], v[116:119], v152, v152 op_sel_hi:[0,0,0]
	v_mfma_scale_f32_16x16x128_f8f6f4 v[92:95], v[154:161], v[16:23], v[142:145], v152, v152 op_sel_hi:[0,0,0]
	v_mfma_scale_f32_16x16x128_f8f6f4 v[112:115], v[134:141], v[16:23], v[112:115], v152, v152 op_sel_hi:[0,0,0]
	v_mfma_scale_f32_16x16x128_f8f6f4 v[84:87], v[162:169], v[16:23], v[178:181], v152, v152 op_sel_hi:[0,0,0]
	s_setprio 0
	s_setprio 1
	v_mfma_scale_f32_16x16x128_f8f6f4 v[104:107], v[0:7], v[24:31], v[104:107], v152, v152 op_sel_hi:[0,0,0]
	v_mfma_scale_f32_16x16x128_f8f6f4 v[76:79], v[154:161], v[24:31], v[182:185], v152, v152 op_sel_hi:[0,0,0]
	v_mfma_scale_f32_16x16x128_f8f6f4 v[96:99], v[134:141], v[24:31], v[186:189], v152, v152 op_sel_hi:[0,0,0]
	v_mfma_scale_f32_16x16x128_f8f6f4 v[72:75], v[162:169], v[24:31], v[190:193], v152, v152 op_sel_hi:[0,0,0]
	v_mfma_scale_f32_16x16x128_f8f6f4 v[88:91], v[0:7], v[32:39], v[194:197], v152, v152 op_sel_hi:[0,0,0]
	v_mfma_scale_f32_16x16x128_f8f6f4 v[68:71], v[154:161], v[32:39], v[198:201], v152, v152 op_sel_hi:[0,0,0]
	v_mfma_scale_f32_16x16x128_f8f6f4 v[80:83], v[134:141], v[32:39], v[210:213], v152, v152 op_sel_hi:[0,0,0]
	v_mfma_scale_f32_16x16x128_f8f6f4 v[60:63], v[162:169], v[32:39], v[60:63], v152, v152 op_sel_hi:[0,0,0]
	s_setprio 0
	s_barrier
	v_mov_b32_e32 v128, v146
	ds_read_b128 v[8:11], v151 offset:49152
	ds_read_b128 v[12:15], v151 offset:49168
	ds_read_b128 v[16:19], v151 offset:51200
	ds_read_b128 v[20:23], v151 offset:51216
	ds_read_b128 v[170:173], v151 offset:53248
	ds_read_b128 v[174:177], v151 offset:53264
	ds_read_b128 v[178:181], v151 offset:55296
	ds_read_b128 v[182:185], v151 offset:55312
	s_add_i32 s16, s16, s86
	v_lshl_add_u64 v[24:25], s[66:67], 0, v[128:129]
	v_lshl_add_u64 v[24:25], v[24:25], 0, s[26:27]
	s_mov_b32 m0, s16
	v_mov_b32_e32 v128, v147
	global_load_lds_dwordx4 v[24:25], off
	s_add_i32 m0, s16, 0x2000
	v_lshl_add_u64 v[24:25], s[66:67], 0, v[128:129]
	v_lshl_add_u64 v[24:25], v[24:25], 0, s[26:27]
	s_add_u32 s60, s66, 0x20080
	global_load_lds_dwordx4 v[24:25], off
	s_addc_u32 s61, s67, 0
	v_mov_b32_e32 v24, v146
	s_add_i32 s16, s17, s86
	s_mov_b32 m0, s16
	v_mov_b32_e32 v128, v146
	global_load_lds_dwordx4 v24, s[60:61]
	v_mov_b32_e32 v24, v147
	s_add_i32 m0, s16, 0x2000
	s_nop 0
	global_load_lds_dwordx4 v24, s[60:61]
	s_mov_b32 m0, s92
	v_lshl_add_u64 v[24:25], s[64:65], 0, v[128:129]
	v_lshl_add_u64 v[24:25], v[24:25], 0, s[26:27]
	v_mov_b32_e32 v128, v147
	global_load_lds_dwordx4 v[24:25], off
	s_mov_b32 m0, s93
	v_lshl_add_u64 v[24:25], s[64:65], 0, v[128:129]
	v_lshl_add_u64 v[24:25], v[24:25], 0, s[26:27]
	global_load_lds_dwordx4 v[24:25], off
	s_waitcnt vmcnt(8)
	s_waitcnt lgkmcnt(0)
	s_barrier
; #define PG8_WAIT_V(n) asm volatile("s_waitcnt vmcnt(" #n ")" ::: "memory")
;     __device__ __forceinline__ void operator()(const f32x4 (&acc)[2][2][4][2], const Unit& u, int wr, int wc, int fr, int fq) const {
;     ...
;             for (int m = 0; m < 4; ++m) { const int row = row0 + ai * HALF + m * 16;
;                 const float* xr = (row < TP ? xp + (size_t)row * DM : xs + (size_t)(row - TP) * DM) + col0;
;                 bf16_t* brow = x1b + (size_t)row * DM + col0; float ss = 0.f;
; #pragma unroll
;                 for (int bj = 0; bj < 2; ++bj)
; #pragma unroll
;                     for (int n = 0; n < 2; ++n) { const int co = bj * HALF + n * 16; const f32x4 v = *(const f32x4*)(xr + co) + acc[ai][bj][m][n] * sc;
; template <class Epi, class SchedT, bool ALIGN_EPI, bool SP2, bool FP8 = false>
; __device__ __forceinline__ void gemm_phase(LAS unsigned char* lds, const Gemm g, const SchedT& S, const Epi& E, const int wid) {
;     ...
;             PG8_WAIT_V(8); PG8_WAIT_L(0); PG8_BAR; PG8_MMAP(1, 1, 1); PG8_BAR; PG8_SCHED;
;             } else {
;             PG8_LDB(B0, 0, 0); PG8_SCHED; PG8_LDA(At, 0, 0); PG8_STAGE(PG8_SA(1, 1), a1 + hstepA, voffA);
;             PG8_WAIT_L(8); PG8_BAR; PG8_WAIT_L(0); PG8_MMA(0, 0, At, B0); PG8_BAR; PG8_SCHED;
;             PG8_LDB(B1, 0, 1); PG8_STAGE(PG8_SB(0, 0), b2, voffB);
;             PG8_BAR; PG8_WAIT_L(0); PG8_MMA(0, 1, At, B1); PG8_BAR;
;             PG8_LDA(At, 0, 1); PG8_STAGE(PG8_SA(0, 0), a2, voffA);
;             PG8_BAR; PG8_WAIT_L(0); PG8_MMA(1, 0, At, B0); PG8_BAR; PG8_SCHED;
;             PG8_STAGE(PG8_SB(0, 1), b2 + hstepB, voffB);
;             PG8_WAIT_V(6); PG8_BAR; PG8_MMA(1, 1, At, B1); PG8_BAR;
;             PG8_LDB(B0, 1, 0); PG8_SCHED; PG8_LDA(At, 1, 0); PG8_STAGE(PG8_SA(0, 1), a2 + hstepA, voffA);
;             PG8_WAIT_L(8); PG8_BAR; PG8_WAIT_L(0); PG8_MMA(0, 0, At, B0); PG8_BAR; PG8_SCHED;
;             PG8_LDB(B1, 1, 1); PG8_STAGE(PG8_SB(1, 0), b3, voffB);
;             PG8_BAR; PG8_WAIT_L(0); PG8_MMA(0, 1, At, B1); PG8_BAR;
;             PG8_LDA(At, 1, 1); PG8_STAGE(PG8_SA(1, 0), a3, voffA);
;             PG8_BAR; PG8_WAIT_L(0); PG8_MMA(1, 0, At, B0); PG8_BAR; PG8_SCHED;
;             PG8_STAGE(PG8_SB(1, 1), b3 + hstepB, voffB);
;             PG8_WAIT_V(6); PG8_BAR; PG8_MMA(1, 1, At, B1); PG8_BAR;
;             }
;         }
;         if constexpr (ALIGN_EPI) { if (wr == 0) PG8_BAR; }
	s_setprio 1
	s_waitcnt lgkmcnt(0)
	v_mfma_scale_f32_16x16x128_f8f6f4 v[64:67], v[0:7], v[8:15], v[64:67], v152, v152 op_sel_hi:[0,0,0]
	v_mfma_scale_f32_16x16x128_f8f6f4 v[44:47], v[154:161], v[8:15], v[44:47], v152, v152 op_sel_hi:[0,0,0]
	v_mfma_scale_f32_16x16x128_f8f6f4 v[56:59], v[134:141], v[8:15], v[56:59], v152, v152 op_sel_hi:[0,0,0]
	v_mfma_scale_f32_16x16x128_f8f6f4 v[36:39], v[162:169], v[8:15], v[202:205], v152, v152 op_sel_hi:[0,0,0]
	v_mfma_scale_f32_16x16x128_f8f6f4 v[52:55], v[0:7], v[16:23], v[52:55], v152, v152 op_sel_hi:[0,0,0]
	v_mfma_scale_f32_16x16x128_f8f6f4 v[28:31], v[154:161], v[16:23], v[206:209], v152, v152 op_sel_hi:[0,0,0]
	v_mfma_scale_f32_16x16x128_f8f6f4 v[48:51], v[134:141], v[16:23], v[48:51], v152, v152 op_sel_hi:[0,0,0]
	v_mfma_scale_f32_16x16x128_f8f6f4 v[20:23], v[162:169], v[16:23], v[214:217], v152, v152 op_sel_hi:[0,0,0]
	s_setprio 0
	s_setprio 1
	v_mfma_scale_f32_16x16x128_f8f6f4 v[40:43], v[0:7], v[170:177], v[40:43], v152, v152 op_sel_hi:[0,0,0]
	v_mfma_scale_f32_16x16x128_f8f6f4 v[12:15], v[154:161], v[170:177], v[218:221], v152, v152 op_sel_hi:[0,0,0]
	v_mfma_scale_f32_16x16x128_f8f6f4 v[32:35], v[134:141], v[170:177], v[222:225], v152, v152 op_sel_hi:[0,0,0]
	v_mfma_scale_f32_16x16x128_f8f6f4 v[8:11], v[162:169], v[170:177], v[226:229], v152, v152 op_sel_hi:[0,0,0]
	v_mfma_scale_f32_16x16x128_f8f6f4 v[24:27], v[0:7], v[178:185], v[230:233], v152, v152 op_sel_hi:[0,0,0]
	v_mfma_scale_f32_16x16x128_f8f6f4 v[4:7], v[154:161], v[178:185], v[234:237], v152, v152 op_sel_hi:[0,0,0]
	v_mfma_scale_f32_16x16x128_f8f6f4 v[16:19], v[134:141], v[178:185], v[238:241], v152, v152 op_sel_hi:[0,0,0]
	v_mfma_scale_f32_16x16x128_f8f6f4 v[0:3], v[162:169], v[178:185], v[242:245], v152, v152 op_sel_hi:[0,0,0]
	s_setprio 0
	s_barrier
	s_add_u32 s52, s52, 0x100
	s_addc_u32 s53, s53, 0
	s_add_u32 s30, s30, 0x100
	s_addc_u32 s31, s31, 0
	s_cmp_ge_i32 s45, s20
	s_mov_b32 s47, s45
	s_cbranch_scc0 .LBB0_779
	v_pk_mul_f32 v[142:143], v[126:127], s[42:43] op_sel_hi:[1,0]
	v_pk_mul_f32 v[144:145], v[124:125], s[42:43] op_sel_hi:[1,0]
	v_pk_mul_f32 v[136:137], v[122:123], s[42:43] op_sel_hi:[1,0]
	v_pk_mul_f32 v[134:135], v[120:121], s[42:43] op_sel_hi:[1,0]
	v_pk_mul_f32 v[140:141], v[110:111], s[42:43] op_sel_hi:[1,0]
	v_pk_mul_f32 v[138:139], v[108:109], s[42:43] op_sel_hi:[1,0]
	v_pk_mul_f32 v[126:127], v[102:103], s[42:43] op_sel_hi:[1,0]
	v_pk_mul_f32 v[124:125], v[100:101], s[42:43] op_sel_hi:[1,0]
	v_pk_mul_f32 v[122:123], v[118:119], s[42:43] op_sel_hi:[1,0]
	v_pk_mul_f32 v[120:121], v[116:117], s[42:43] op_sel_hi:[1,0]
	v_pk_mul_f32 v[114:115], v[114:115], s[42:43] op_sel_hi:[1,0]
	v_pk_mul_f32 v[112:113], v[112:113], s[42:43] op_sel_hi:[1,0]
	v_pk_mul_f32 v[118:119], v[94:95], s[42:43] op_sel_hi:[1,0]
	v_pk_mul_f32 v[116:117], v[92:93], s[42:43] op_sel_hi:[1,0]
	v_pk_mul_f32 v[110:111], v[86:87], s[42:43] op_sel_hi:[1,0]
	v_pk_mul_f32 v[108:109], v[84:85], s[42:43] op_sel_hi:[1,0]
	v_pk_mul_f32 v[106:107], v[106:107], s[42:43] op_sel_hi:[1,0]
	v_pk_mul_f32 v[104:105], v[104:105], s[42:43] op_sel_hi:[1,0]
	v_pk_mul_f32 v[98:99], v[98:99], s[42:43] op_sel_hi:[1,0]
	v_pk_mul_f32 v[96:97], v[96:97], s[42:43] op_sel_hi:[1,0]
	v_pk_mul_f32 v[102:103], v[78:79], s[42:43] op_sel_hi:[1,0]
	v_pk_mul_f32 v[100:101], v[76:77], s[42:43] op_sel_hi:[1,0]
	v_pk_mul_f32 v[94:95], v[74:75], s[42:43] op_sel_hi:[1,0]
	v_pk_mul_f32 v[92:93], v[72:73], s[42:43] op_sel_hi:[1,0]
	v_pk_mul_f32 v[90:91], v[90:91], s[42:43] op_sel_hi:[1,0]
	v_pk_mul_f32 v[88:89], v[88:89], s[42:43] op_sel_hi:[1,0]
	v_pk_mul_f32 v[82:83], v[82:83], s[42:43] op_sel_hi:[1,0]
	v_pk_mul_f32 v[80:81], v[80:81], s[42:43] op_sel_hi:[1,0]
	v_pk_mul_f32 v[86:87], v[70:71], s[42:43] op_sel_hi:[1,0]
	v_pk_mul_f32 v[84:85], v[68:69], s[42:43] op_sel_hi:[1,0]
	v_pk_mul_f32 v[78:79], v[62:63], s[42:43] op_sel_hi:[1,0]
	v_pk_mul_f32 v[76:77], v[60:61], s[42:43] op_sel_hi:[1,0]
	v_pk_mul_f32 v[74:75], v[66:67], s[42:43] op_sel_hi:[1,0]
	v_pk_mul_f32 v[72:73], v[64:65], s[42:43] op_sel_hi:[1,0]
	v_pk_mul_f32 v[66:67], v[58:59], s[42:43] op_sel_hi:[1,0]
	v_pk_mul_f32 v[64:65], v[56:57], s[42:43] op_sel_hi:[1,0]
	v_pk_mul_f32 v[70:71], v[46:47], s[42:43] op_sel_hi:[1,0]
	v_pk_mul_f32 v[68:69], v[44:45], s[42:43] op_sel_hi:[1,0]
	v_pk_mul_f32 v[62:63], v[38:39], s[42:43] op_sel_hi:[1,0]
	v_pk_mul_f32 v[60:61], v[36:37], s[42:43] op_sel_hi:[1,0]
	v_pk_mul_f32 v[58:59], v[54:55], s[42:43] op_sel_hi:[1,0]
	v_pk_mul_f32 v[56:57], v[52:53], s[42:43] op_sel_hi:[1,0]
	v_pk_mul_f32 v[50:51], v[50:51], s[42:43] op_sel_hi:[1,0]
	v_pk_mul_f32 v[48:49], v[48:49], s[42:43] op_sel_hi:[1,0]
	v_pk_mul_f32 v[54:55], v[30:31], s[42:43] op_sel_hi:[1,0]
	v_pk_mul_f32 v[52:53], v[28:29], s[42:43] op_sel_hi:[1,0]
	v_pk_mul_f32 v[46:47], v[22:23], s[42:43] op_sel_hi:[1,0]
	v_pk_mul_f32 v[44:45], v[20:21], s[42:43] op_sel_hi:[1,0]
	v_pk_mul_f32 v[38:39], v[42:43], s[42:43] op_sel_hi:[1,0]
	v_pk_mul_f32 v[36:37], v[40:41], s[42:43] op_sel_hi:[1,0]
	v_pk_mul_f32 v[30:31], v[34:35], s[42:43] op_sel_hi:[1,0]
	v_pk_mul_f32 v[28:29], v[32:33], s[42:43] op_sel_hi:[1,0]
	v_pk_mul_f32 v[34:35], v[14:15], s[42:43] op_sel_hi:[1,0]
	v_pk_mul_f32 v[32:33], v[12:13], s[42:43] op_sel_hi:[1,0]
	v_pk_mul_f32 v[22:23], v[10:11], s[42:43] op_sel_hi:[1,0]
	v_pk_mul_f32 v[20:21], v[8:9], s[42:43] op_sel_hi:[1,0]
	v_pk_mul_f32 v[14:15], v[26:27], s[42:43] op_sel_hi:[1,0]
	v_pk_mul_f32 v[12:13], v[24:25], s[42:43] op_sel_hi:[1,0]
	v_pk_mul_f32 v[10:11], v[18:19], s[42:43] op_sel_hi:[1,0]
	v_pk_mul_f32 v[8:9], v[16:17], s[42:43] op_sel_hi:[1,0]
	v_pk_mul_f32 v[6:7], v[6:7], s[42:43] op_sel_hi:[1,0]
	v_pk_mul_f32 v[4:5], v[4:5], s[42:43] op_sel_hi:[1,0]
	v_pk_mul_f32 v[2:3], v[2:3], s[42:43] op_sel_hi:[1,0]
	v_pk_mul_f32 v[0:1], v[0:1], s[42:43] op_sel_hi:[1,0]
	s_and_b64 vcc, exec, s[96:97]
	s_cbranch_vccz .LBB0_782
